# v58 + attention item epilogue: the 8 subln_g loads issued together (counted vmcnt) + bias-lut global load no longer waited before the K/V tile DMAs are issued
# baseline (speedup 1.0000x reference)
.LBB0_526:
	v_ashrrev_i32_e32 v0, 2, v153
	v_and_b32_e32 v46, 3, v153
	v_lshlrev_b32_e32 v2, 9, v0
	v_lshlrev_b32_e32 v44, 7, v46
	v_add3_u32 v40, 0, v2, v44
	s_waitcnt lgkmcnt(0)
	s_barrier
	ds_read_b128 v[30:33], v40
	ds_read_b128 v[26:29], v40 offset:16
	ds_read_b128 v[22:25], v40 offset:32
	ds_read_b128 v[18:21], v40 offset:48
	ds_read_b128 v[14:17], v40 offset:64
	ds_read_b128 v[10:13], v40 offset:80
	s_waitcnt lgkmcnt(5)
	v_mov_b32_e32 v4, v31
	s_waitcnt lgkmcnt(4)
	v_mov_b32_e32 v5, v27
	v_mov_b32_e32 v2, v30
	v_mov_b32_e32 v3, v26
	v_pk_mul_f32 v[4:5], v[4:5], v[4:5]
	s_lshl_b64 s[4:5], s[44:45], 25
	v_pk_fma_f32 v[2:3], v[2:3], v[2:3], v[4:5]
	v_mov_b32_e32 v4, v32
	v_mov_b32_e32 v5, v28
	v_pk_fma_f32 v[2:3], v[4:5], v[4:5], v[2:3]
	v_mov_b32_e32 v4, v33
	v_mov_b32_e32 v5, v29
	v_pk_fma_f32 v[34:35], v[4:5], v[4:5], v[2:3]
	s_waitcnt lgkmcnt(3)
	v_mov_b32_e32 v4, v23
	s_waitcnt lgkmcnt(2)
	v_mov_b32_e32 v5, v19
	v_mov_b32_e32 v2, v22
	v_mov_b32_e32 v3, v18
	v_pk_mul_f32 v[4:5], v[4:5], v[4:5]
	v_add_f32_e32 v34, v34, v35
	v_pk_fma_f32 v[2:3], v[2:3], v[2:3], v[4:5]
	v_mov_b32_e32 v4, v24
	v_mov_b32_e32 v5, v20
	v_pk_fma_f32 v[2:3], v[4:5], v[4:5], v[2:3]
	v_mov_b32_e32 v4, v25
	v_mov_b32_e32 v5, v21
	v_pk_fma_f32 v[36:37], v[4:5], v[4:5], v[2:3]
	s_waitcnt lgkmcnt(1)
	v_mov_b32_e32 v4, v15
	s_waitcnt lgkmcnt(0)
	v_mov_b32_e32 v5, v11
	v_mov_b32_e32 v2, v14
	v_mov_b32_e32 v3, v10
	v_pk_mul_f32 v[4:5], v[4:5], v[4:5]
	v_add_f32_e32 v34, v34, v36
	v_pk_fma_f32 v[2:3], v[2:3], v[2:3], v[4:5]
	v_mov_b32_e32 v4, v16
	v_mov_b32_e32 v5, v12
	v_pk_fma_f32 v[2:3], v[4:5], v[4:5], v[2:3]
	v_mov_b32_e32 v4, v17
	v_mov_b32_e32 v5, v13
	v_pk_fma_f32 v[38:39], v[4:5], v[4:5], v[2:3]
	ds_read_b128 v[6:9], v40 offset:96
	ds_read_b128 v[2:5], v40 offset:112
	v_add_f32_e32 v34, v34, v37
	v_add_f32_e32 v34, v34, v38
	v_add_f32_e32 v34, v34, v39
	s_waitcnt lgkmcnt(1)
	v_mov_b32_e32 v42, v7
	s_waitcnt lgkmcnt(0)
	v_mov_b32_e32 v43, v3
	v_mov_b32_e32 v40, v6
	v_mov_b32_e32 v41, v2
	v_pk_mul_f32 v[42:43], v[42:43], v[42:43]
	v_readlane_b32 s8, v254, 60
	v_pk_fma_f32 v[40:41], v[40:41], v[40:41], v[42:43]
	v_mov_b32_e32 v42, v8
	v_mov_b32_e32 v43, v4
	v_pk_fma_f32 v[40:41], v[42:43], v[42:43], v[40:41]
	v_mov_b32_e32 v42, v9
	v_mov_b32_e32 v43, v5
	v_pk_fma_f32 v[40:41], v[42:43], v[42:43], v[40:41]
	v_readlane_b32 s9, v254, 61
	v_add_f32_e32 v34, v34, v40
	v_add_f32_e32 v34, v34, v41
	ds_bpermute_b32 v35, v149, v34
	s_add_u32 s4, s8, s4
	s_addc_u32 s5, s9, s5
	s_lshl_b32 s6, s84, 8
	s_add_u32 s4, s4, s6
	s_waitcnt lgkmcnt(0)
	v_add_f32_e32 v34, v34, v35
	ds_bpermute_b32 v35, v150, v34
	v_readlane_b32 s10, v254, 62
	v_readlane_b32 s11, v254, 63
	s_addc_u32 s5, s5, 0
	s_add_i32 s53, s53, s88
	s_waitcnt lgkmcnt(0)
	v_add_f32_e32 v34, v34, v35
	v_fmamk_f32 v34, v34, 0x3c000000, v144
	v_cmp_gt_f32_e32 vcc, s66, v34
	v_mul_f32_e32 v35, 0x4b800000, v34
	s_cmpk_gt_i32 s53, 0x7ff
	v_cndmask_b32_e32 v34, v34, v35, vcc
	v_rsq_f32_e32 v34, v34
	s_nop 0
	v_mul_f32_e32 v35, 0x45800000, v34
	v_cndmask_b32_e32 v34, v34, v35, vcc
	v_mul_f32_e32 v45, 0x3f24fd5c, v34
	v_add_u32_e32 v34, s85, v0
	v_ashrrev_i32_e32 v35, 31, v34
	v_lshlrev_b64 v[34:35], 11, v[34:35]
	v_lshl_add_u64 v[34:35], s[4:5], 0, v[34:35]
	v_readlane_b32 s4, v254, 32
	v_lshlrev_b32_e32 v0, 6, v46
	v_readlane_b32 s5, v254, 33
	v_lshl_add_u64 v[42:43], v[34:35], 0, v[0:1]
	s_nop 3
	global_load_dwordx4 v[34:37], v44, s[4:5] offset:16
	global_load_dwordx4 v[38:41], v44, s[4:5]
	global_load_dwordx4 v[220:223], v44, s[4:5] offset:48
	global_load_dwordx4 v[224:227], v44, s[4:5] offset:32
	global_load_dwordx4 v[228:231], v44, s[4:5] offset:80
	global_load_dwordx4 v[232:235], v44, s[4:5] offset:64
	global_load_dwordx4 v[236:239], v44, s[4:5] offset:112
	global_load_dwordx4 v[240:243], v44, s[4:5] offset:96
	v_mul_f32_e32 v26, v26, v45
	v_mul_f32_e32 v0, v30, v45
	v_mul_f32_e32 v30, v31, v45
	v_mul_f32_e32 v31, v32, v45
	v_mul_f32_e32 v32, v33, v45
	v_mul_f32_e32 v18, v18, v45
	v_mul_f32_e32 v10, v10, v45
	v_mul_f32_e32 v2, v2, v45
	v_readlane_b32 s6, v254, 34
	v_readlane_b32 s7, v254, 35
	v_readlane_b32 s8, v254, 36
	v_readlane_b32 s9, v254, 37
	v_readlane_b32 s10, v254, 38
	v_readlane_b32 s11, v254, 39
	v_readlane_b32 s12, v254, 40
	v_readlane_b32 s13, v254, 41
	v_readlane_b32 s14, v254, 42
	v_readlane_b32 s15, v254, 43
	v_readlane_b32 s16, v254, 44
	v_readlane_b32 s17, v254, 45
	v_readlane_b32 s18, v254, 46
	v_readlane_b32 s19, v254, 47
	s_waitcnt vmcnt(7)
	v_mul_f32_e32 v33, v34, v26
	v_mul_f32_e32 v26, v27, v45
	v_mul_f32_e32 v34, v35, v26
	v_mul_f32_e32 v26, v28, v45
	v_mul_f32_e32 v35, v36, v26
	v_mul_f32_e32 v26, v29, v45
	v_mul_f32_e32 v29, v37, v26
	s_waitcnt vmcnt(6)
	v_mul_f32_e32 v0, v38, v0
	v_mul_f32_e32 v30, v39, v30
	v_mul_f32_e32 v31, v40, v31
	v_mul_f32_e32 v32, v41, v32
	v_cvt_pk_bf16_f32 v26, v0, v30
	v_cvt_pk_bf16_f32 v27, v31, v32
	v_cvt_pk_bf16_f32 v28, v33, v34
	v_cvt_pk_bf16_f32 v29, v35, v29
	global_store_dwordx4 v[42:43], v[26:29], off
	s_waitcnt vmcnt(5)
	s_nop 1
	v_mov_b32_e32 v26, v220
	v_mov_b32_e32 v27, v221
	v_mov_b32_e32 v28, v222
	v_mov_b32_e32 v29, v223
	s_nop 0
	v_mov_b32_e32 v30, v224
	v_mov_b32_e32 v31, v225
	v_mov_b32_e32 v32, v226
	v_mov_b32_e32 v33, v227
	v_mul_f32_e32 v0, v22, v45
	v_mul_f32_e32 v22, v23, v45
	v_mul_f32_e32 v23, v24, v45
	v_mul_f32_e32 v24, v25, v45
	v_mul_f32_e32 v25, v26, v18
	v_mul_f32_e32 v18, v19, v45
	v_mul_f32_e32 v26, v27, v18
	v_mul_f32_e32 v18, v20, v45
	v_mul_f32_e32 v27, v28, v18
	v_mul_f32_e32 v18, v21, v45
	v_mul_f32_e32 v21, v29, v18
	v_mul_f32_e32 v0, v30, v0
	v_mul_f32_e32 v22, v31, v22
	v_mul_f32_e32 v23, v32, v23
	v_mul_f32_e32 v24, v33, v24
	v_cvt_pk_bf16_f32 v18, v0, v22
	v_cvt_pk_bf16_f32 v19, v23, v24
	v_cvt_pk_bf16_f32 v20, v25, v26
	v_cvt_pk_bf16_f32 v21, v27, v21
	global_store_dwordx4 v[42:43], v[18:21], off offset:16
	s_waitcnt vmcnt(4)
	s_nop 1
	v_mov_b32_e32 v18, v228
	v_mov_b32_e32 v19, v229
	v_mov_b32_e32 v20, v230
	v_mov_b32_e32 v21, v231
	s_nop 0
	v_mov_b32_e32 v22, v232
	v_mov_b32_e32 v23, v233
	v_mov_b32_e32 v24, v234
	v_mov_b32_e32 v25, v235
	v_mul_f32_e32 v0, v14, v45
	v_mul_f32_e32 v14, v15, v45
	v_mul_f32_e32 v15, v16, v45
	v_mul_f32_e32 v16, v17, v45
	v_mul_f32_e32 v17, v10, v18
	v_mul_f32_e32 v10, v11, v45
	v_mul_f32_e32 v18, v10, v19
	v_mul_f32_e32 v10, v12, v45
	v_mul_f32_e32 v19, v10, v20
	v_mul_f32_e32 v10, v13, v45
	v_mul_f32_e32 v13, v10, v21
	v_mul_f32_e32 v0, v22, v0
	v_mul_f32_e32 v14, v23, v14
	v_mul_f32_e32 v15, v24, v15
	v_mul_f32_e32 v16, v25, v16
	v_cvt_pk_bf16_f32 v10, v0, v14
	v_cvt_pk_bf16_f32 v11, v15, v16
	v_cvt_pk_bf16_f32 v12, v17, v18
	v_cvt_pk_bf16_f32 v13, v19, v13
	global_store_dwordx4 v[42:43], v[10:13], off offset:32
	s_waitcnt vmcnt(3)
	s_nop 1
	v_mov_b32_e32 v10, v236
	v_mov_b32_e32 v11, v237
	v_mov_b32_e32 v12, v238
	v_mov_b32_e32 v13, v239
	s_nop 0
	v_mov_b32_e32 v14, v240
	v_mov_b32_e32 v15, v241
	v_mov_b32_e32 v16, v242
	v_mov_b32_e32 v17, v243
	v_mul_f32_e32 v0, v6, v45
	v_mul_f32_e32 v6, v7, v45
	v_mul_f32_e32 v7, v8, v45
	v_mul_f32_e32 v8, v9, v45
	v_mul_f32_e32 v9, v2, v10
	v_mul_f32_e32 v2, v3, v45
	v_mul_f32_e32 v10, v2, v11
	v_mul_f32_e32 v2, v4, v45
	v_mul_f32_e32 v11, v2, v12
	v_mul_f32_e32 v2, v5, v45
	v_mul_f32_e32 v5, v2, v13
	v_mul_f32_e32 v0, v0, v14
	v_mul_f32_e32 v6, v6, v15
	v_mul_f32_e32 v7, v7, v16
	v_mul_f32_e32 v8, v8, v17
	v_cvt_pk_bf16_f32 v2, v0, v6
	v_cvt_pk_bf16_f32 v3, v7, v8
	v_cvt_pk_bf16_f32 v4, v9, v10
	v_cvt_pk_bf16_f32 v5, v11, v5
	global_store_dwordx4 v[42:43], v[2:5], off offset:48
	s_cbranch_scc1 .LBB0_628
.LBB0_527:
	s_ashr_i32 s4, s53, 31
	s_lshr_b32 s4, s4, 25
	s_add_i32 s4, s53, s4
	s_ashr_i32 s87, s4, 7
	v_mov_b32_e32 v153, v197
	s_movk_i32 s4, 0x101
	s_and_b32 s84, s87, 7
	s_waitcnt lgkmcnt(0)
	v_cmp_gt_i32_e32 vcc, s4, v153
	s_barrier
	s_and_saveexec_b64 s[4:5], vcc
	s_cbranch_execz .LBB0_529
	v_add_u32_e32 v0, 0xffffff80, v153
	v_sub_u32_e32 v2, 0x80, v153
	v_max_i32_e32 v0, v0, v2
	v_max_u32_e32 v2, 1, v0
	v_cvt_f32_u32_e32 v2, v2
	s_mov_b32 s6, 0x3f317217
	v_readlane_b32 s36, v254, 32
	v_readlane_b32 s40, v254, 36
	v_mul_f32_e32 v2, 0x3e000000, v2
	v_cmp_gt_f32_e32 vcc, s66, v2
	v_readlane_b32 s41, v254, 37
	v_readlane_b32 s38, v254, 34
	v_cndmask_b32_e64 v3, 0, 32, vcc
	v_ldexp_f32 v2, v2, v3
	v_log_f32_e32 v2, v2
	v_cndmask_b32_e32 v3, 0, v145, vcc
	v_readlane_b32 s39, v254, 35
	s_mov_b64 s[38:39], 0x43fc000
	v_mul_f32_e32 v4, 0x3f317217, v2
	v_fma_f32 v4, v2, s6, -v4
	v_fmac_f32_e32 v4, 0x3377d1cf, v2
	s_mov_b32 s6, 0x7f800000
	v_fmac_f32_e32 v4, 0x3f317217, v2
	v_cmp_lt_f32_e64 vcc, |v2|, s6
	v_readlane_b32 s37, v254, 33
	v_readlane_b32 s42, v254, 38
	v_cndmask_b32_e32 v2, v2, v4, vcc
	v_sub_f32_e32 v2, v2, v3
	v_div_scale_f32 v3, s[6:7], s67, s67, v2
	v_rcp_f32_e32 v4, v3
	v_div_scale_f32 v5, vcc, v2, s67, v2
	v_readlane_b32 s43, v254, 39
	v_fma_f32 v6, -v3, v4, 1.0
	v_fmac_f32_e32 v4, v6, v4
	v_mul_f32_e32 v6, v5, v4
	v_fma_f32 v7, -v3, v6, v5
	v_fmac_f32_e32 v6, v7, v4
	v_fma_f32 v3, -v3, v6, v5
	v_div_fmas_f32 v3, v3, v4, v6
	v_div_fixup_f32 v2, v3, s67, v2
	v_mul_f32_e32 v2, 0x41000000, v2
	v_cvt_i32_f32_e32 v2, v2
	v_cmp_lt_i32_e32 vcc, s64, v153
	v_readlane_b32 s44, v254, 40
	v_readlane_b32 s45, v254, 41
	v_min_i32_e32 v2, 7, v2
	v_cndmask_b32_e64 v3, 0, 16, vcc
	v_add_u32_e32 v2, 8, v2
	v_cmp_gt_u32_e32 vcc, 8, v0
	v_readlane_b32 s46, v254, 42
	v_readlane_b32 s47, v254, 43
	v_cndmask_b32_e32 v0, v2, v0, vcc
	v_add_u32_e32 v0, v0, v3
	v_lshl_or_b32 v2, v0, 3, s84
	v_ashrrev_i32_e32 v3, 31, v2
	v_lshl_add_u64 v[2:3], v[2:3], 2, s[40:41]
	global_load_dword v252, v[2:3], off
	v_lshl_add_u32 v253, v153, 2, 0
	v_add_u32_e32 v253, 0x18800, v253
	v_readlane_b32 s48, v254, 44
	v_readlane_b32 s49, v254, 45
	v_readlane_b32 s50, v254, 46
	v_readlane_b32 s51, v254, 47
.LBB0_529:
	s_or_b64 exec, exec, s[4:5]
	s_ashr_i32 s44, s87, 3
	s_lshl_b32 s4, s87, 7
	s_ashr_i32 s45, s44, 31
	s_sub_i32 s86, s53, s4
	s_lshl_b32 s96, s84, 23
	s_lshl_b64 s[36:37], s[44:45], 22
	s_add_u32 s4, s92, s36
	s_addc_u32 s5, s93, s37
	s_add_u32 s4, s4, s96
	s_addc_u32 s5, s5, 0
	s_add_u32 s48, s4, 0x4000000
	s_addc_u32 s49, s5, 0
	s_lshl_b32 s85, s86, 7
	s_lshl_b32 s6, s84, 2
	v_and_b32_e32 v154, 31, v153
	v_mov_b32_e32 v0, s6
	s_or_b32 s6, s85, s71
	v_or_b32_e32 v132, s6, v154
	v_ashrrev_i32_e32 v133, 31, v132
	v_readlane_b32 s8, v254, 32
	v_lshlrev_b64 v[2:3], 8, v[132:133]
	v_bfe_u32 v155, v153, 5, 1
	v_readlane_b32 s12, v254, 36
	v_readlane_b32 s13, v254, 37
	v_lshl_add_u64 v[2:3], s[4:5], 0, v[2:3]
	v_bfe_u32 v140, v153, 4, 2
	s_nop 2
	global_load_dword v6, v0, s[12:13] offset:480
	global_load_dword v7, v0, s[12:13] offset:992
	v_lshl_add_u64 v[2:3], v[2:3], 0, s[26:27]
	v_lshlrev_b32_e32 v130, 4, v155
	v_mov_b32_e32 v131, v1
	v_or_b32_e32 v0, s62, v140
	v_lshl_add_u64 v[2:3], v[2:3], 0, v[130:131]
	v_lshlrev_b32_e32 v8, 4, v153
	v_lshlrev_b32_e32 v161, 4, v0
	global_load_dwordx4 v[110:113], v[2:3], off
	global_load_dwordx4 v[106:109], v[2:3], off offset:32
	global_load_dwordx4 v[102:105], v[2:3], off offset:64
	global_load_dwordx4 v[98:101], v[2:3], off offset:96
	v_and_b32_e32 v160, 0xf0, v8
	v_lshlrev_b32_e32 v2, 8, v0
	v_and_b32_e32 v0, 0x70, v161
	v_bitop3_b32 v0, v0, v2, v160 bitop3:0xde
	v_bfe_u32 v2, v153, 2, 3
	s_mov_b32 s6, 0xffffff3
	v_bitop3_b32 v141, v2, s6, v148 bitop3:0xc8
	v_lshrrev_b32_e32 v2, 1, v153
	v_readlane_b32 s18, v254, 42
	s_cmp_lg_u32 0, -1
	v_and_b32_e32 v143, 8, v2
	v_or_b32_e32 v3, s73, v155
	v_and_b32_e32 v159, 48, v8
	v_readlane_b32 s9, v254, 33
	s_cselect_b32 s18, 0, 0
	v_or3_b32 v2, v141, v143, s72
	v_lshl_or_b32 v3, v3, 6, v159
	s_add_i32 s7, s74, 0xc000
	v_lshl_or_b32 v2, v2, 8, v3
	s_mov_b32 m0, s7
	v_lshl_add_u64 v[134:135], s[4:5], 0, v[0:1]
	s_mov_b64 s[8:9], 0x4002000
	s_add_i32 s6, s74, 0xe000
	v_mov_b32_e32 v3, v1
	global_load_lds_dwordx4 v0, s[48:49]
	v_lshl_add_u64 v[4:5], v[134:135], 0, s[8:9]
	s_mov_b32 m0, s6
	v_lshl_add_u64 v[136:137], s[4:5], 0, v[2:3]
	s_mov_b64 s[4:5], 0x8000000
	global_load_lds_dwordx4 v[4:5], off
	v_lshl_add_u64 v[2:3], v[136:137], 0, s[4:5]
	s_mov_b32 m0, s74
	s_mov_b64 s[4:5], 0x8002000
	global_load_lds_dwordx4 v[2:3], off
	v_lshl_add_u64 v[2:3], v[136:137], 0, s[4:5]
	s_add_i32 m0, s74, 0x2000
	s_mov_b64 s[4:5], 0x4004000
	global_load_lds_dwordx4 v[2:3], off
	v_lshl_add_u64 v[2:3], v[134:135], 0, s[4:5]
	s_add_i32 m0, s74, 0x10000
	s_mov_b64 s[4:5], 0x4006000
	global_load_lds_dwordx4 v[2:3], off
	v_lshl_add_u64 v[2:3], v[134:135], 0, s[4:5]
	s_add_i32 m0, s74, 0x12000
	s_mov_b64 s[4:5], 0x4008000
	global_load_lds_dwordx4 v[2:3], off
	s_waitcnt vmcnt(0) lgkmcnt(0)
	v_cmp_gt_i32_e32 vcc, 0x101, v153
	s_and_saveexec_b64 s[100:101], vcc
	v_mul_f32_e32 v252, 0x3fb8aa3b, v252
	ds_write_b32 v253, v252
	s_or_b64 exec, exec, s[100:101]
	s_waitcnt lgkmcnt(0)
	s_barrier
	v_lshl_add_u64 v[2:3], v[134:135], 0, s[4:5]
	s_add_i32 m0, s74, 0x14000
	s_mov_b64 s[4:5], 0x400a000
	global_load_lds_dwordx4 v[2:3], off
	v_lshl_add_u64 v[2:3], v[134:135], 0, s[4:5]
	s_add_i32 m0, s74, 0x16000
	s_mov_b64 s[4:5], 0x8004000
	global_load_lds_dwordx4 v[2:3], off
	v_lshl_add_u64 v[2:3], v[136:137], 0, s[4:5]
	s_add_i32 m0, s74, 0x4000
	s_mov_b64 s[4:5], 0x8006000
	global_load_lds_dwordx4 v[2:3], off
	v_lshl_add_u64 v[2:3], v[136:137], 0, s[4:5]
	s_add_i32 m0, s74, 0x6000
	v_lshlrev_b32_e32 v4, 6, v153
	global_load_lds_dwordx4 v[2:3], off
	v_lshlrev_b32_e32 v2, 3, v153
	v_and_b32_e32 v3, 0xc0, v8
	v_and_or_b32 v2, v2, 24, v3
	v_lshlrev_b32_e32 v3, 1, v153
	v_and_b32_e32 v3, 32, v3
	v_and_b32_e32 v4, 0x800, v4
	v_or3_b32 v2, v2, v3, v4
	v_lshlrev_b32_e32 v156, 8, v154
	v_lshlrev_b32_e32 v164, 4, v154
	v_and_b32_e32 v131, 63, v153
	s_waitcnt vmcnt(0)
	v_mul_f32_e32 v142, 0x3fb8aa3b, v6
	v_mul_f32_e32 v133, 0x3fb8aa3b, v7
	v_add_u32_e32 v157, s18, v2
	s_mov_b64 s[4:5], -1
	s_and_b64 vcc, exec, s[28:29]
	v_and_b32_e32 v162, 0x70, v164
	v_add_u32_e32 v163, 0, v156
	v_lshlrev_b32_e32 v158, 2, v155
	v_readlane_b32 s10, v254, 34
	v_readlane_b32 s11, v254, 35
	v_readlane_b32 s14, v254, 38
	v_readlane_b32 s15, v254, 39
	v_readlane_b32 s16, v254, 40
	v_readlane_b32 s17, v254, 41
	v_readlane_b32 s19, v254, 43
	v_readlane_b32 s20, v254, 44
	v_readlane_b32 s21, v254, 45
	v_readlane_b32 s22, v254, 46
	v_readlane_b32 s23, v254, 47
	s_branch .LBB0_562
	v_bitop3_b32 v167, v130, v162, s64 bitop3:0x36
	v_add_u32_e32 v6, v163, v167
	ds_read_b128 v[2:5], v6 offset:49152
	ds_read_b128 v[6:9], v6 offset:57344
	s_movk_i32 s4, 0xa0
	v_bitop3_b32 v168, v130, v162, s4 bitop3:0x36
	v_add_u32_e32 v38, v163, v168
	s_waitcnt lgkmcnt(0)
	v_mfma_f32_32x32x16_bf16 v[18:33], v[2:5], v[110:113], 0
	ds_read_b128 v[34:37], v38 offset:49152
	ds_read_b128 v[38:41], v38 offset:57344
	s_movk_i32 s4, 0xc0
	v_bitop3_b32 v169, v130, v162, s4 bitop3:0x36
	v_add_u32_e32 v42, v163, v169
	s_movk_i32 s4, 0xe0
	v_bitop3_b32 v170, v130, v162, s4 bitop3:0x36
	v_add_u32_e32 v46, v163, v170
	v_mfma_f32_32x32x16_bf16 v[2:17], v[6:9], v[110:113], 0
	s_mov_b64 s[4:5], 0x400c000
	s_mov_b32 m0, s7
	v_sub_u32_e32 v166, v158, v132
	s_waitcnt lgkmcnt(1)
	v_mfma_f32_32x32x16_bf16 v[18:33], v[34:37], v[106:109], v[18:33]
	ds_read_b128 v[34:37], v42 offset:49152
	ds_read_b128 v[42:45], v42 offset:57344
	s_waitcnt lgkmcnt(2)
	v_mfma_f32_32x32x16_bf16 v[2:17], v[38:41], v[106:109], v[2:17]
	ds_read_b128 v[38:41], v46 offset:49152
	ds_read_b128 v[46:49], v46 offset:57344
	s_waitcnt vmcnt(4) lgkmcnt(0)
	s_barrier
	s_waitcnt lgkmcnt(3)
	v_mfma_f32_32x32x16_bf16 v[18:33], v[34:37], v[102:105], v[18:33]
	v_lshl_add_u64 v[34:35], v[134:135], 0, s[4:5]
	s_mov_b64 s[4:5], 0x400e000
	global_load_lds_dwordx4 v[34:35], off
	v_lshl_add_u64 v[34:35], v[134:135], 0, s[4:5]
	s_mov_b32 m0, s6
	s_mov_b64 s[4:5], 0x8008000
	global_load_lds_dwordx4 v[34:35], off
	v_lshl_add_u64 v[34:35], v[136:137], 0, s[4:5]
	s_mov_b32 m0, s81
	s_mov_b64 s[4:5], 0x800a000
	global_load_lds_dwordx4 v[34:35], off
	v_lshl_add_u64 v[34:35], v[136:137], 0, s[4:5]
	s_mov_b32 m0, s82
	s_waitcnt lgkmcnt(0)
	v_mfma_f32_32x32x16_bf16 v[2:17], v[42:45], v[102:105], v[2:17]
	global_load_lds_dwordx4 v[34:35], off
	s_add_i32 s4, s85, 0xd9
	s_cmpk_gt_u32 s4, 0x172
	v_mfma_f32_32x32x16_bf16 v[18:33], v[38:41], v[98:101], v[18:33]
	v_mfma_f32_32x32x16_bf16 v[2:17], v[46:49], v[98:101], v[2:17]
	s_cbranch_scc1 .LBB0_532
	v_mov_b32_e32 v58, v166
	s_add_i32 s4, 0, 0x18800
	v_add_u32_e32 v36, 1, v58
	v_med3_i32 v37, v36, s65, v146
	v_med3_i32 v36, v36, s69, v147
	v_lshl_add_u32 v38, v36, 2, s4
	v_add_u32_e32 v36, 2, v58
	v_med3_i32 v39, v36, s65, v146
	v_med3_i32 v36, v36, s69, v147
	v_lshl_add_u32 v40, v36, 2, s4
	v_add_u32_e32 v36, 3, v58
	v_med3_i32 v34, v58, s65, v146
	v_med3_i32 v35, v58, s69, v147
	v_med3_i32 v41, v36, s65, v146
	v_med3_i32 v36, v36, s69, v147
	v_lshl_add_u32 v34, v34, 2, s4
	v_lshl_add_u32 v35, v35, 2, s4
	v_lshl_add_u32 v37, v37, 2, s4
	v_lshl_add_u32 v39, v39, 2, s4
	v_lshl_add_u32 v41, v41, 2, s4
	v_lshl_add_u32 v42, v36, 2, s4
	ds_read_b32 v34, v34 offset:512
	ds_read_b32 v36, v35 offset:640
	ds_read_b32 v35, v37 offset:512
	ds_read_b32 v37, v38 offset:640
	ds_read_b32 v38, v39 offset:512
	ds_read_b32 v40, v40 offset:640
	ds_read_b32 v39, v41 offset:512
	ds_read_b32 v41, v42 offset:640
	v_add_u32_e32 v42, 8, v58
	v_med3_i32 v43, v42, s65, v146
	v_med3_i32 v42, v42, s69, v147
	v_lshl_add_u32 v44, v42, 2, s4
	v_add_u32_e32 v42, 9, v58
	v_med3_i32 v45, v42, s65, v146
	v_med3_i32 v42, v42, s69, v147
	v_lshl_add_u32 v46, v42, 2, s4
	v_add_u32_e32 v42, 10, v58
	v_med3_i32 v47, v42, s65, v146
	v_med3_i32 v42, v42, s69, v147
	v_lshl_add_u32 v48, v42, 2, s4
	v_add_u32_e32 v42, 11, v58
	v_med3_i32 v49, v42, s65, v146
	v_med3_i32 v42, v42, s69, v147
	v_lshl_add_u32 v43, v43, 2, s4
	v_lshl_add_u32 v45, v45, 2, s4
	v_lshl_add_u32 v47, v47, 2, s4
	v_lshl_add_u32 v49, v49, 2, s4
	v_lshl_add_u32 v50, v42, 2, s4
	ds_read_b32 v42, v43 offset:512
	ds_read_b32 v44, v44 offset:640
	ds_read_b32 v43, v45 offset:512
	ds_read_b32 v45, v46 offset:640
	ds_read_b32 v46, v47 offset:512
	ds_read_b32 v48, v48 offset:640
	ds_read_b32 v47, v49 offset:512
	ds_read_b32 v49, v50 offset:640
	v_add_u32_e32 v50, 16, v58
	v_med3_i32 v51, v50, s65, v146
	v_med3_i32 v50, v50, s69, v147
	v_lshl_add_u32 v52, v50, 2, s4
	v_add_u32_e32 v50, 17, v58
	v_med3_i32 v53, v50, s65, v146
	v_med3_i32 v50, v50, s69, v147
	v_lshl_add_u32 v54, v50, 2, s4
	v_add_u32_e32 v50, 18, v58
	v_med3_i32 v55, v50, s65, v146
	v_med3_i32 v50, v50, s69, v147
	v_lshl_add_u32 v56, v50, 2, s4
	v_add_u32_e32 v50, 19, v58
	v_add_u32_e32 v61, 25, v58
	v_med3_i32 v57, v50, s65, v146
	v_med3_i32 v50, v50, s69, v147
	v_med3_i32 v62, v61, s65, v146
	v_lshl_add_u32 v51, v51, 2, s4
	v_lshl_add_u32 v53, v53, 2, s4
	v_lshl_add_u32 v55, v55, 2, s4
	v_lshl_add_u32 v57, v57, 2, s4
	v_lshl_add_u32 v59, v50, 2, s4
	v_lshl_add_u32 v64, v62, 2, s4
	v_add_u32_e32 v62, 26, v58
	ds_read_b32 v50, v51 offset:512
	ds_read_b32 v52, v52 offset:640
	ds_read_b32 v51, v53 offset:512
	ds_read_b32 v53, v54 offset:640
	ds_read_b32 v54, v55 offset:512
	ds_read_b32 v56, v56 offset:640
	ds_read_b32 v55, v57 offset:512
	ds_read_b32 v57, v59 offset:640
	v_add_u32_e32 v59, 24, v58
	v_med3_i32 v63, v62, s65, v146
	v_med3_i32 v62, v62, s69, v147
	v_add_u32_e32 v58, 27, v58
	v_med3_i32 v60, v59, s65, v146
	v_med3_i32 v59, v59, s69, v147
	v_med3_i32 v61, v61, s69, v147
	v_lshl_add_u32 v66, v62, 2, s4
	v_med3_i32 v62, v58, s65, v146
	v_lshl_add_u32 v60, v60, 2, s4
	v_lshl_add_u32 v59, v59, 2, s4
	v_lshl_add_u32 v61, v61, 2, s4
	v_lshl_add_u32 v63, v63, 2, s4
	v_med3_i32 v58, v58, s69, v147
	v_lshl_add_u32 v65, v62, 2, s4
	v_lshl_add_u32 v67, v58, 2, s4
	ds_read_b32 v58, v60 offset:512
	ds_read_b32 v60, v59 offset:640
	ds_read_b32 v62, v63 offset:512
	ds_read_b32 v63, v65 offset:512
	ds_read_b32 v59, v64 offset:512
	ds_read_b32 v65, v67 offset:640
	ds_read_b32 v64, v66 offset:640
	ds_read_b32 v61, v61 offset:640
	s_waitcnt lgkmcnt(0)
	v_pk_add_f32 v[32:33], v[32:33], v[62:63]
	v_pk_add_f32 v[30:31], v[30:31], v[58:59]
	v_pk_add_f32 v[28:29], v[28:29], v[54:55]
	v_pk_add_f32 v[26:27], v[26:27], v[50:51]
	v_pk_add_f32 v[24:25], v[24:25], v[46:47]
	v_pk_add_f32 v[22:23], v[22:23], v[42:43]
	v_pk_add_f32 v[20:21], v[20:21], v[38:39]
	v_pk_add_f32 v[18:19], v[18:19], v[34:35]
	v_pk_add_f32 v[16:17], v[16:17], v[64:65]
	v_pk_add_f32 v[14:15], v[14:15], v[60:61]
	v_pk_add_f32 v[12:13], v[12:13], v[56:57]
	v_pk_add_f32 v[10:11], v[10:11], v[52:53]
	v_pk_add_f32 v[8:9], v[8:9], v[48:49]
	v_pk_add_f32 v[6:7], v[6:7], v[44:45]
	v_pk_add_f32 v[4:5], v[4:5], v[40:41]
	v_pk_add_f32 v[2:3], v[2:3], v[36:37]

.LBB0_686:
	v_ashrrev_i32_e32 v0, 2, v153
	v_and_b32_e32 v54, 3, v153
	v_lshlrev_b32_e32 v2, 9, v0
	v_lshlrev_b32_e32 v44, 7, v54
	v_readlane_b32 s12, v254, 32
	v_add3_u32 v45, 0, v2, v44
	v_readlane_b32 s13, v254, 33
	s_waitcnt lgkmcnt(0)
	s_barrier
	ds_read_b128 v[14:17], v45
	ds_read_b128 v[10:13], v45 offset:16
	ds_read_b128 v[6:9], v45 offset:32
	ds_read_b128 v[2:5], v45 offset:48
	global_load_dwordx4 v[26:29], v44, s[12:13] offset:16
	global_load_dwordx4 v[38:41], v44, s[12:13]
	global_load_dwordx4 v[220:223], v44, s[12:13] offset:32
	global_load_dwordx4 v[224:227], v44, s[12:13] offset:48
	global_load_dwordx4 v[228:231], v44, s[12:13] offset:64
	global_load_dwordx4 v[232:235], v44, s[12:13] offset:80
	global_load_dwordx4 v[236:239], v44, s[12:13] offset:96
	global_load_dwordx4 v[240:243], v44, s[12:13] offset:112
	s_waitcnt lgkmcnt(3)
	v_mov_b32_e32 v20, v15
	s_waitcnt lgkmcnt(2)
	v_mov_b32_e32 v21, v11
	v_mov_b32_e32 v18, v14
	v_mov_b32_e32 v19, v10
	v_pk_mul_f32 v[20:21], v[20:21], v[20:21]
	ds_read_b128 v[34:37], v45 offset:64
	ds_read_b128 v[30:33], v45 offset:80
	v_pk_fma_f32 v[18:19], v[18:19], v[18:19], v[20:21]
	v_mov_b32_e32 v20, v16
	v_mov_b32_e32 v21, v12
	v_pk_fma_f32 v[18:19], v[20:21], v[20:21], v[18:19]
	v_mov_b32_e32 v20, v17
	v_mov_b32_e32 v21, v13
	v_pk_fma_f32 v[42:43], v[20:21], v[20:21], v[18:19]
	s_waitcnt lgkmcnt(3)
	v_mov_b32_e32 v20, v7
	s_waitcnt lgkmcnt(2)
	v_mov_b32_e32 v21, v3
	v_mov_b32_e32 v18, v6
	v_mov_b32_e32 v19, v2
	v_pk_mul_f32 v[20:21], v[20:21], v[20:21]
	s_waitcnt lgkmcnt(1)
	v_mov_b32_e32 v50, v37
	v_pk_fma_f32 v[18:19], v[18:19], v[18:19], v[20:21]
	v_mov_b32_e32 v20, v8
	v_mov_b32_e32 v21, v4
	v_pk_fma_f32 v[18:19], v[20:21], v[20:21], v[18:19]
	v_mov_b32_e32 v20, v9
	v_mov_b32_e32 v21, v5
	v_pk_fma_f32 v[46:47], v[20:21], v[20:21], v[18:19]
	v_mov_b32_e32 v20, v35
	s_waitcnt lgkmcnt(0)
	v_mov_b32_e32 v21, v31
	v_mov_b32_e32 v18, v34
	v_mov_b32_e32 v19, v30
	v_pk_mul_f32 v[20:21], v[20:21], v[20:21]
	v_mov_b32_e32 v51, v33
	v_pk_fma_f32 v[18:19], v[18:19], v[18:19], v[20:21]
	v_mov_b32_e32 v20, v36
	v_mov_b32_e32 v21, v32
	v_pk_fma_f32 v[48:49], v[20:21], v[20:21], v[18:19]
	ds_read_b128 v[22:25], v45 offset:96
	ds_read_b128 v[18:21], v45 offset:112
	v_add_f32_e32 v42, v42, v43
	v_pk_fma_f32 v[48:49], v[50:51], v[50:51], v[48:49]
	v_add_f32_e32 v42, v42, v46
	s_waitcnt lgkmcnt(1)
	v_mov_b32_e32 v52, v23
	s_waitcnt lgkmcnt(0)
	v_mov_b32_e32 v53, v19
	v_mov_b32_e32 v50, v22
	v_mov_b32_e32 v51, v18
	v_pk_mul_f32 v[52:53], v[52:53], v[52:53]
	v_add_f32_e32 v42, v42, v47
	v_pk_fma_f32 v[50:51], v[50:51], v[50:51], v[52:53]
	v_mov_b32_e32 v52, v24
	v_mov_b32_e32 v53, v20
	v_pk_fma_f32 v[50:51], v[52:53], v[52:53], v[50:51]
	v_mov_b32_e32 v52, v25
	v_mov_b32_e32 v53, v21
	v_add_f32_e32 v42, v42, v48
	v_pk_fma_f32 v[50:51], v[52:53], v[52:53], v[50:51]
	v_add_f32_e32 v42, v42, v49
	v_add_f32_e32 v42, v42, v50
	v_add_f32_e32 v42, v42, v51
	ds_bpermute_b32 v43, v149, v42
	s_lshl_b64 s[4:5], s[40:41], 24
	v_readlane_b32 s8, v254, 60
	v_readlane_b32 s9, v254, 61
	s_add_u32 s4, s8, s4
	s_waitcnt lgkmcnt(0)
	v_add_f32_e32 v42, v42, v43
	ds_bpermute_b32 v43, v150, v42
	s_addc_u32 s5, s9, s5
	s_lshl_b32 s6, s79, 8
	s_add_u32 s4, s4, s6
	s_addc_u32 s5, s5, 0
	s_waitcnt lgkmcnt(0)
	v_add_f32_e32 v42, v42, v43
	v_fmamk_f32 v42, v42, 0x3c000000, v144
	v_mul_f32_e32 v43, 0x4b800000, v42
	v_cmp_gt_f32_e32 vcc, s62, v42
	s_add_i32 s48, s48, s88
	s_cmpk_gt_i32 s48, 0x7ff
	v_cndmask_b32_e32 v42, v42, v43, vcc
	v_rsq_f32_e32 v42, v42
	v_readlane_b32 s14, v254, 34
	v_readlane_b32 s15, v254, 35
	v_readlane_b32 s16, v254, 36
	v_mul_f32_e32 v43, 0x45800000, v42
	v_cndmask_b32_e32 v42, v42, v43, vcc
	v_mul_f32_e32 v45, 0x3f24fd5c, v42
	v_add_u32_e32 v42, s80, v0
	v_ashrrev_i32_e32 v43, 31, v42
	v_lshlrev_b64 v[42:43], 11, v[42:43]
	v_lshl_add_u64 v[42:43], s[4:5], 0, v[42:43]
	v_lshlrev_b32_e32 v0, 6, v54
	v_mul_f32_e32 v10, v10, v45
	v_lshl_add_u64 v[42:43], v[42:43], 0, v[0:1]
	v_mul_f32_e32 v0, v14, v45
	v_mul_f32_e32 v14, v15, v45
	v_mul_f32_e32 v15, v16, v45
	v_mul_f32_e32 v16, v17, v45
	s_waitcnt vmcnt(7)
	v_mul_f32_e32 v17, v26, v10
	v_mul_f32_e32 v10, v11, v45
	v_mul_f32_e32 v26, v27, v10
	v_mul_f32_e32 v10, v12, v45
	s_waitcnt vmcnt(6)
	v_mul_f32_e32 v14, v39, v14
	v_mul_f32_e32 v27, v28, v10
	v_mul_f32_e32 v10, v13, v45
	s_brev_b32 s4, 32
	v_mul_f32_e32 v0, v38, v0
	v_mul_f32_e32 v15, v40, v15
	v_mul_f32_e32 v13, v29, v10
	v_cvt_pk_bf16_f32 v10, v0, v14
	v_add_co_u32_e32 v14, vcc, s4, v42
	v_mul_f32_e32 v16, v41, v16
	v_cvt_pk_bf16_f32 v11, v15, v16
	s_nop 0
	v_addc_co_u32_e32 v15, vcc, 0, v43, vcc
	v_cvt_pk_bf16_f32 v12, v17, v26
	v_cvt_pk_bf16_f32 v13, v27, v13
	global_store_dwordx4 v[14:15], v[10:13], off
	s_waitcnt vmcnt(5)
	s_nop 1
	v_mov_b32_e32 v12, v220
	v_mov_b32_e32 v13, v221
	v_mov_b32_e32 v14, v222
	v_mov_b32_e32 v15, v223
	s_nop 0
	v_mov_b32_e32 v26, v224
	v_mov_b32_e32 v27, v225
	v_mov_b32_e32 v28, v226
	v_mov_b32_e32 v29, v227
	s_mov_b64 s[4:5], 0x4000000
	v_mul_f32_e32 v5, v5, v45
	v_lshl_add_u64 v[10:11], v[42:43], 0, s[4:5]
	v_mul_f32_e32 v0, v6, v45
	v_mul_f32_e32 v6, v7, v45
	v_mul_f32_e32 v7, v8, v45
	v_mul_f32_e32 v8, v9, v45
	v_mul_f32_e32 v2, v2, v45
	v_mul_f32_e32 v3, v3, v45
	v_mul_f32_e32 v4, v4, v45
	v_mul_f32_e32 v16, v31, v45
	v_mul_f32_e32 v17, v32, v45
	v_readlane_b32 s17, v254, 37
	v_readlane_b32 s18, v254, 38
	v_readlane_b32 s19, v254, 39
	v_readlane_b32 s20, v254, 40
	v_readlane_b32 s21, v254, 41
	v_readlane_b32 s22, v254, 42
	v_readlane_b32 s23, v254, 43
	v_readlane_b32 s24, v254, 44
	v_readlane_b32 s25, v254, 45
	v_readlane_b32 s26, v254, 46
	v_readlane_b32 s27, v254, 47
	v_readlane_b32 s10, v254, 62
	v_readlane_b32 s11, v254, 63
	v_mul_f32_e32 v0, v12, v0
	v_mul_f32_e32 v5, v29, v5
	v_mul_f32_e32 v6, v13, v6
	v_mul_f32_e32 v7, v14, v7
	v_mul_f32_e32 v8, v15, v8
	v_mul_f32_e32 v9, v26, v2
	v_mul_f32_e32 v12, v27, v3
	v_mul_f32_e32 v13, v28, v4
	v_cvt_pk_bf16_f32 v2, v0, v6
	v_cvt_pk_bf16_f32 v3, v7, v8
	v_cvt_pk_bf16_f32 v4, v9, v12
	v_cvt_pk_bf16_f32 v5, v13, v5
	global_store_dwordx4 v[10:11], v[2:5], off offset:16
	s_waitcnt vmcnt(4)
	s_nop 1
	v_mov_b32_e32 v2, v228
	v_mov_b32_e32 v3, v229
	v_mov_b32_e32 v4, v230
	v_mov_b32_e32 v5, v231
	s_nop 0
	v_mov_b32_e32 v6, v232
	v_mov_b32_e32 v7, v233
	v_mov_b32_e32 v8, v234
	v_mov_b32_e32 v9, v235
	v_mul_f32_e32 v0, v34, v45
	v_mul_f32_e32 v12, v35, v45
	v_mul_f32_e32 v13, v36, v45
	v_mul_f32_e32 v14, v37, v45
	v_mul_f32_e32 v15, v30, v45
	v_mul_f32_e32 v26, v33, v45
	v_mul_f32_e32 v0, v2, v0
	v_mul_f32_e32 v2, v3, v12
	v_mul_f32_e32 v3, v4, v13
	v_mul_f32_e32 v4, v5, v14
	v_mul_f32_e32 v5, v15, v6
	v_mul_f32_e32 v6, v16, v7
	v_mul_f32_e32 v7, v17, v8
	v_mul_f32_e32 v8, v26, v9
	v_cvt_pk_bf16_f32 v2, v0, v2
	v_cvt_pk_bf16_f32 v3, v3, v4
	v_cvt_pk_bf16_f32 v4, v5, v6
	v_cvt_pk_bf16_f32 v5, v7, v8
	global_store_dwordx4 v[10:11], v[2:5], off offset:32
	s_waitcnt vmcnt(3)
	s_nop 1
	v_mov_b32_e32 v2, v236
	v_mov_b32_e32 v3, v237
	v_mov_b32_e32 v4, v238
	v_mov_b32_e32 v5, v239
	s_nop 0
	v_mov_b32_e32 v6, v240
	v_mov_b32_e32 v7, v241
	v_mov_b32_e32 v8, v242
	v_mov_b32_e32 v9, v243
	v_mul_f32_e32 v0, v22, v45
	v_mul_f32_e32 v12, v23, v45
	v_mul_f32_e32 v13, v24, v45
	v_mul_f32_e32 v14, v25, v45
	v_mul_f32_e32 v15, v18, v45
	v_mul_f32_e32 v16, v19, v45
	v_mul_f32_e32 v17, v20, v45
	v_mul_f32_e32 v18, v21, v45
	v_mul_f32_e32 v0, v0, v2
	v_mul_f32_e32 v2, v12, v3
	v_mul_f32_e32 v3, v13, v4
	v_mul_f32_e32 v4, v14, v5
	v_mul_f32_e32 v5, v15, v6
	v_mul_f32_e32 v6, v16, v7
	v_mul_f32_e32 v7, v17, v8
	v_mul_f32_e32 v8, v18, v9
	v_cvt_pk_bf16_f32 v2, v0, v2
	v_cvt_pk_bf16_f32 v3, v3, v4
	v_cvt_pk_bf16_f32 v4, v5, v6
	v_cvt_pk_bf16_f32 v5, v7, v8
	global_store_dwordx4 v[10:11], v[2:5], off offset:48
	s_cbranch_scc1 .LBB0_788
.LBB0_687:
	s_ashr_i32 s4, s48, 31
	s_lshr_b32 s4, s4, 26
	s_add_i32 s4, s48, s4
	s_ashr_i32 s82, s4, 6
	v_mov_b32_e32 v153, v197
	s_movk_i32 s4, 0x101
	s_and_b32 s79, s82, 7
	s_waitcnt lgkmcnt(0)
	v_cmp_gt_i32_e32 vcc, s4, v153
	s_barrier
	s_and_saveexec_b64 s[4:5], vcc
	s_cbranch_execz .LBB0_689
	v_add_u32_e32 v0, 0xffffff80, v153
	v_sub_u32_e32 v2, 0x80, v153
	v_max_i32_e32 v0, v0, v2
	v_max_u32_e32 v2, 1, v0
	v_cvt_f32_u32_e32 v2, v2
	s_mov_b32 s6, 0x3f317217
	s_mov_b32 s7, 0x7f800000
	v_readlane_b32 s8, v254, 32
	v_mul_f32_e32 v2, 0x3e000000, v2
	v_cmp_gt_f32_e32 vcc, s62, v2
	v_readlane_b32 s12, v254, 36
	v_readlane_b32 s13, v254, 37
	v_cndmask_b32_e64 v3, 0, 32, vcc
	v_ldexp_f32 v2, v2, v3
	v_log_f32_e32 v2, v2
	v_cndmask_b32_e32 v3, 0, v145, vcc
	v_readlane_b32 s9, v254, 33
	v_readlane_b32 s10, v254, 34
	v_mul_f32_e32 v4, 0x3f317217, v2
	v_fma_f32 v4, v2, s6, -v4
	v_fmac_f32_e32 v4, 0x3377d1cf, v2
	v_fmac_f32_e32 v4, 0x3f317217, v2
	v_cmp_lt_f32_e64 vcc, |v2|, s7
	v_readlane_b32 s11, v254, 35
	v_readlane_b32 s14, v254, 38
	v_cndmask_b32_e32 v2, v2, v4, vcc
	v_sub_f32_e32 v2, v2, v3
	v_div_scale_f32 v3, s[6:7], s63, s63, v2
	v_rcp_f32_e32 v4, v3
	v_div_scale_f32 v5, vcc, v2, s63, v2
	v_readlane_b32 s15, v254, 39
	v_fma_f32 v6, -v3, v4, 1.0
	v_fmac_f32_e32 v4, v6, v4
	v_mul_f32_e32 v6, v5, v4
	v_fma_f32 v7, -v3, v6, v5
	v_fmac_f32_e32 v6, v7, v4
	v_fma_f32 v3, -v3, v6, v5
	v_div_fmas_f32 v3, v3, v4, v6
	v_div_fixup_f32 v2, v3, s63, v2
	v_mul_f32_e32 v2, 0x41000000, v2
	v_cvt_i32_f32_e32 v2, v2
	v_cmp_lt_i32_e32 vcc, s51, v153
	v_readlane_b32 s16, v254, 40
	v_readlane_b32 s17, v254, 41
	v_min_i32_e32 v2, 7, v2
	v_cndmask_b32_e64 v3, 0, 16, vcc
	v_add_u32_e32 v2, 8, v2
	v_cmp_gt_u32_e32 vcc, 8, v0
	v_readlane_b32 s18, v254, 42
	v_readlane_b32 s19, v254, 43
	v_cndmask_b32_e32 v0, v2, v0, vcc
	v_add_u32_e32 v0, v0, v3
	v_lshl_or_b32 v2, v0, 3, s79
	v_ashrrev_i32_e32 v3, 31, v2
	v_lshl_add_u64 v[2:3], v[2:3], 2, s[12:13]
	global_load_dword v252, v[2:3], off
	v_lshl_add_u32 v253, v153, 2, 0
	v_add_u32_e32 v253, 0x18800, v253
	v_readlane_b32 s20, v254, 44
	v_readlane_b32 s21, v254, 45
	v_readlane_b32 s22, v254, 46
	v_readlane_b32 s23, v254, 47
.LBB0_689:
	s_or_b64 exec, exec, s[4:5]
	s_ashr_i32 s40, s82, 3
	s_lshl_b32 s4, s82, 6
	s_ashr_i32 s41, s40, 31
	s_sub_i32 s81, s48, s4
	s_lshl_b32 s83, s79, 23
	s_lshl_b64 s[10:11], s[40:41], 21
	s_add_u32 s4, s92, s10
	s_addc_u32 s5, s93, s11
	s_add_u32 s4, s4, s83
	s_addc_u32 s5, s5, 0
	s_add_u32 s44, s4, 0x4000000
	s_addc_u32 s45, s5, 0
	s_lshl_b32 s80, s81, 7
	s_lshl_b32 s6, s79, 2
	v_and_b32_e32 v154, 31, v153
	v_mov_b32_e32 v0, s6
	s_or_b32 s6, s80, s67
	v_or_b32_e32 v132, s6, v154
	v_ashrrev_i32_e32 v133, 31, v132
	v_readlane_b32 s12, v254, 32
	v_lshlrev_b64 v[2:3], 8, v[132:133]
	v_bfe_u32 v155, v153, 5, 1
	v_readlane_b32 s16, v254, 36
	v_readlane_b32 s17, v254, 37
	v_lshl_add_u64 v[2:3], s[4:5], 0, v[2:3]
	v_bfe_u32 v140, v153, 4, 2
	s_nop 2
	global_load_dword v6, v0, s[16:17] offset:480
	global_load_dword v7, v0, s[16:17] offset:992
	v_lshl_add_u64 v[2:3], v[2:3], 0, s[28:29]
	v_lshlrev_b32_e32 v130, 4, v155
	v_mov_b32_e32 v131, v1
	v_or_b32_e32 v0, s49, v140
	v_lshl_add_u64 v[2:3], v[2:3], 0, v[130:131]
	v_lshlrev_b32_e32 v8, 4, v153
	v_lshlrev_b32_e32 v161, 4, v0
	global_load_dwordx4 v[110:113], v[2:3], off
	global_load_dwordx4 v[106:109], v[2:3], off offset:32
	global_load_dwordx4 v[102:105], v[2:3], off offset:64
	global_load_dwordx4 v[98:101], v[2:3], off offset:96
	v_and_b32_e32 v160, 0xf0, v8
	v_lshlrev_b32_e32 v2, 8, v0
	v_and_b32_e32 v0, 0x70, v161
	v_bitop3_b32 v0, v0, v2, v160 bitop3:0xde
	v_bfe_u32 v2, v153, 2, 3
	s_mov_b32 s6, 0xffffff3
	v_bitop3_b32 v141, v2, s6, v148 bitop3:0xc8
	v_lshrrev_b32_e32 v2, 1, v153
	v_readlane_b32 s18, v254, 38
	s_cmp_lg_u32 0, -1
	v_and_b32_e32 v143, 8, v2
	v_or_b32_e32 v3, s69, v155
	v_and_b32_e32 v159, 48, v8
	s_cselect_b32 s18, 0, 0
	v_or3_b32 v2, v141, v143, s68
	v_lshl_or_b32 v3, v3, 6, v159
	s_add_i32 s7, s70, 0xc000
	v_lshl_or_b32 v2, v2, 8, v3
	s_mov_b32 m0, s7
	v_lshl_add_u64 v[134:135], s[4:5], 0, v[0:1]
	s_mov_b64 s[8:9], 0x4002000
	s_add_i32 s6, s70, 0xe000
	v_mov_b32_e32 v3, v1
	global_load_lds_dwordx4 v0, s[44:45]
	v_lshl_add_u64 v[4:5], v[134:135], 0, s[8:9]
	s_mov_b32 m0, s6
	v_lshl_add_u64 v[136:137], s[4:5], 0, v[2:3]
	s_mov_b64 s[4:5], 0x8000000
	global_load_lds_dwordx4 v[4:5], off
	v_lshl_add_u64 v[2:3], v[136:137], 0, s[4:5]
	s_mov_b32 m0, s70
	s_mov_b64 s[4:5], 0x8002000
	global_load_lds_dwordx4 v[2:3], off
	v_lshl_add_u64 v[2:3], v[136:137], 0, s[4:5]
	s_add_i32 m0, s70, 0x2000
	s_mov_b64 s[4:5], 0x4004000
	global_load_lds_dwordx4 v[2:3], off
	v_lshl_add_u64 v[2:3], v[134:135], 0, s[4:5]
	s_add_i32 m0, s70, 0x10000
	s_mov_b64 s[4:5], 0x4006000
	global_load_lds_dwordx4 v[2:3], off
	v_lshl_add_u64 v[2:3], v[134:135], 0, s[4:5]
	s_add_i32 m0, s70, 0x12000
	s_mov_b64 s[4:5], 0x4008000
	global_load_lds_dwordx4 v[2:3], off
	s_waitcnt vmcnt(0) lgkmcnt(0)
	v_cmp_gt_i32_e32 vcc, 0x101, v153
	s_and_saveexec_b64 s[100:101], vcc
	v_mul_f32_e32 v252, 0x3fb8aa3b, v252
	ds_write_b32 v253, v252
	s_or_b64 exec, exec, s[100:101]
	s_waitcnt lgkmcnt(0)
	s_barrier
	v_lshl_add_u64 v[2:3], v[134:135], 0, s[4:5]
	s_add_i32 m0, s70, 0x14000
	s_mov_b64 s[4:5], 0x400a000
	global_load_lds_dwordx4 v[2:3], off
	v_lshl_add_u64 v[2:3], v[134:135], 0, s[4:5]
	s_add_i32 m0, s70, 0x16000
	s_mov_b64 s[4:5], 0x8004000
	global_load_lds_dwordx4 v[2:3], off
	v_lshl_add_u64 v[2:3], v[136:137], 0, s[4:5]
	s_add_i32 m0, s70, 0x4000
	s_mov_b64 s[4:5], 0x8006000
	global_load_lds_dwordx4 v[2:3], off
	v_lshl_add_u64 v[2:3], v[136:137], 0, s[4:5]
	s_add_i32 m0, s70, 0x6000
	v_lshlrev_b32_e32 v4, 6, v153
	global_load_lds_dwordx4 v[2:3], off
	v_lshlrev_b32_e32 v2, 3, v153
	v_and_b32_e32 v3, 0xc0, v8
	v_and_or_b32 v2, v2, 24, v3
	v_lshlrev_b32_e32 v3, 1, v153
	v_and_b32_e32 v3, 32, v3
	v_and_b32_e32 v4, 0x800, v4
	v_or3_b32 v2, v2, v3, v4
	v_lshlrev_b32_e32 v156, 8, v154
	v_lshlrev_b32_e32 v164, 4, v154
	v_and_b32_e32 v131, 63, v153
	s_waitcnt vmcnt(0)
	v_mul_f32_e32 v142, 0x3fb8aa3b, v6
	v_mul_f32_e32 v133, 0x3fb8aa3b, v7
	v_add_u32_e32 v157, s18, v2
	s_mov_b64 s[4:5], -1
	s_and_b64 vcc, exec, s[36:37]
	v_and_b32_e32 v162, 0x70, v164
	v_add_u32_e32 v163, 0, v156
	v_lshlrev_b32_e32 v158, 2, v155
	v_readlane_b32 s13, v254, 33
	v_readlane_b32 s14, v254, 34
	v_readlane_b32 s15, v254, 35
	v_readlane_b32 s19, v254, 39
	v_readlane_b32 s20, v254, 40
	v_readlane_b32 s21, v254, 41
	v_readlane_b32 s22, v254, 42
	v_readlane_b32 s23, v254, 43
	v_readlane_b32 s24, v254, 44
	v_readlane_b32 s25, v254, 45
	v_readlane_b32 s26, v254, 46
	v_readlane_b32 s27, v254, 47
	s_branch .LBB0_722
	v_bitop3_b32 v167, v130, v162, s51 bitop3:0x36
	v_add_u32_e32 v6, v163, v167
	ds_read_b128 v[2:5], v6 offset:49152
	ds_read_b128 v[6:9], v6 offset:57344
	s_movk_i32 s4, 0xa0
	v_bitop3_b32 v168, v130, v162, s4 bitop3:0x36
	v_add_u32_e32 v38, v163, v168
	s_waitcnt lgkmcnt(0)
	v_mfma_f32_32x32x16_bf16 v[18:33], v[2:5], v[110:113], 0
	ds_read_b128 v[34:37], v38 offset:49152
	ds_read_b128 v[38:41], v38 offset:57344
	s_movk_i32 s4, 0xc0
	v_bitop3_b32 v169, v130, v162, s4 bitop3:0x36
	v_add_u32_e32 v42, v163, v169
	s_movk_i32 s4, 0xe0
	v_bitop3_b32 v170, v130, v162, s4 bitop3:0x36
	v_add_u32_e32 v46, v163, v170
	v_mfma_f32_32x32x16_bf16 v[2:17], v[6:9], v[110:113], 0
	s_mov_b64 s[4:5], 0x400c000
	s_mov_b32 m0, s7
	v_sub_u32_e32 v166, v158, v132
	s_waitcnt lgkmcnt(1)
	v_mfma_f32_32x32x16_bf16 v[18:33], v[34:37], v[106:109], v[18:33]
	ds_read_b128 v[34:37], v42 offset:49152
	ds_read_b128 v[42:45], v42 offset:57344
	s_waitcnt lgkmcnt(2)
	v_mfma_f32_32x32x16_bf16 v[2:17], v[38:41], v[106:109], v[2:17]
	ds_read_b128 v[38:41], v46 offset:49152
	ds_read_b128 v[46:49], v46 offset:57344
	s_waitcnt vmcnt(4) lgkmcnt(0)
	s_barrier
	s_waitcnt lgkmcnt(3)
	v_mfma_f32_32x32x16_bf16 v[18:33], v[34:37], v[102:105], v[18:33]
	v_lshl_add_u64 v[34:35], v[134:135], 0, s[4:5]
	s_mov_b64 s[4:5], 0x400e000
	global_load_lds_dwordx4 v[34:35], off
	v_lshl_add_u64 v[34:35], v[134:135], 0, s[4:5]
	s_mov_b32 m0, s6
	s_mov_b64 s[4:5], 0x8008000
	global_load_lds_dwordx4 v[34:35], off
	v_lshl_add_u64 v[34:35], v[136:137], 0, s[4:5]
	s_mov_b32 m0, s76
	s_mov_b64 s[4:5], 0x800a000
	global_load_lds_dwordx4 v[34:35], off
	v_lshl_add_u64 v[34:35], v[136:137], 0, s[4:5]
	s_mov_b32 m0, s77
	s_waitcnt lgkmcnt(0)
	v_mfma_f32_32x32x16_bf16 v[2:17], v[42:45], v[102:105], v[2:17]
	global_load_lds_dwordx4 v[34:35], off
	s_add_i32 s4, s80, 0xd9
	s_cmpk_gt_u32 s4, 0x172
	v_mfma_f32_32x32x16_bf16 v[18:33], v[38:41], v[98:101], v[18:33]
	v_mfma_f32_32x32x16_bf16 v[2:17], v[46:49], v[98:101], v[2:17]
	s_cbranch_scc1 .LBB0_692
	v_mov_b32_e32 v58, v166
	s_add_i32 s4, 0, 0x18800
	v_add_u32_e32 v36, 1, v58
	v_med3_i32 v37, v36, s53, v146
	v_med3_i32 v36, v36, s65, v147
	v_lshl_add_u32 v38, v36, 2, s4
	v_add_u32_e32 v36, 2, v58
	v_med3_i32 v39, v36, s53, v146
	v_med3_i32 v36, v36, s65, v147
	v_lshl_add_u32 v40, v36, 2, s4
	v_add_u32_e32 v36, 3, v58
	v_med3_i32 v34, v58, s53, v146
	v_med3_i32 v35, v58, s65, v147
	v_med3_i32 v41, v36, s53, v146
	v_med3_i32 v36, v36, s65, v147
	v_lshl_add_u32 v34, v34, 2, s4
	v_lshl_add_u32 v35, v35, 2, s4
	v_lshl_add_u32 v37, v37, 2, s4
	v_lshl_add_u32 v39, v39, 2, s4
	v_lshl_add_u32 v41, v41, 2, s4
	v_lshl_add_u32 v42, v36, 2, s4
	ds_read_b32 v34, v34 offset:512
	ds_read_b32 v36, v35 offset:640
	ds_read_b32 v35, v37 offset:512
	ds_read_b32 v37, v38 offset:640
	ds_read_b32 v38, v39 offset:512
	ds_read_b32 v40, v40 offset:640
	ds_read_b32 v39, v41 offset:512
	ds_read_b32 v41, v42 offset:640
	v_add_u32_e32 v42, 8, v58
	v_med3_i32 v43, v42, s53, v146
	v_med3_i32 v42, v42, s65, v147
	v_lshl_add_u32 v44, v42, 2, s4
	v_add_u32_e32 v42, 9, v58
	v_med3_i32 v45, v42, s53, v146
	v_med3_i32 v42, v42, s65, v147
	v_lshl_add_u32 v46, v42, 2, s4
	v_add_u32_e32 v42, 10, v58
	v_med3_i32 v47, v42, s53, v146
	v_med3_i32 v42, v42, s65, v147
	v_lshl_add_u32 v48, v42, 2, s4
	v_add_u32_e32 v42, 11, v58
	v_med3_i32 v49, v42, s53, v146
	v_med3_i32 v42, v42, s65, v147
	v_lshl_add_u32 v43, v43, 2, s4
	v_lshl_add_u32 v45, v45, 2, s4
	v_lshl_add_u32 v47, v47, 2, s4
	v_lshl_add_u32 v49, v49, 2, s4
	v_lshl_add_u32 v50, v42, 2, s4
	ds_read_b32 v42, v43 offset:512
	ds_read_b32 v44, v44 offset:640
	ds_read_b32 v43, v45 offset:512
	ds_read_b32 v45, v46 offset:640
	ds_read_b32 v46, v47 offset:512
	ds_read_b32 v48, v48 offset:640
	ds_read_b32 v47, v49 offset:512
	ds_read_b32 v49, v50 offset:640
	v_add_u32_e32 v50, 16, v58
	v_med3_i32 v51, v50, s53, v146
	v_med3_i32 v50, v50, s65, v147
	v_lshl_add_u32 v52, v50, 2, s4
	v_add_u32_e32 v50, 17, v58
	v_med3_i32 v53, v50, s53, v146
	v_med3_i32 v50, v50, s65, v147
	v_lshl_add_u32 v54, v50, 2, s4
	v_add_u32_e32 v50, 18, v58
	v_med3_i32 v55, v50, s53, v146
	v_med3_i32 v50, v50, s65, v147
	v_lshl_add_u32 v56, v50, 2, s4
	v_add_u32_e32 v50, 19, v58
	v_add_u32_e32 v61, 25, v58
	v_med3_i32 v57, v50, s53, v146
	v_med3_i32 v50, v50, s65, v147
	v_med3_i32 v62, v61, s53, v146
	v_lshl_add_u32 v51, v51, 2, s4
	v_lshl_add_u32 v53, v53, 2, s4
	v_lshl_add_u32 v55, v55, 2, s4
	v_lshl_add_u32 v57, v57, 2, s4
	v_lshl_add_u32 v59, v50, 2, s4
	v_lshl_add_u32 v64, v62, 2, s4
	v_add_u32_e32 v62, 26, v58
	ds_read_b32 v50, v51 offset:512
	ds_read_b32 v52, v52 offset:640
	ds_read_b32 v51, v53 offset:512
	ds_read_b32 v53, v54 offset:640
	ds_read_b32 v54, v55 offset:512
	ds_read_b32 v56, v56 offset:640
	ds_read_b32 v55, v57 offset:512
	ds_read_b32 v57, v59 offset:640
	v_add_u32_e32 v59, 24, v58
	v_med3_i32 v63, v62, s53, v146
	v_med3_i32 v62, v62, s65, v147
	v_add_u32_e32 v58, 27, v58
	v_med3_i32 v60, v59, s53, v146
	v_med3_i32 v59, v59, s65, v147
	v_med3_i32 v61, v61, s65, v147
	v_lshl_add_u32 v66, v62, 2, s4
	v_med3_i32 v62, v58, s53, v146
	v_lshl_add_u32 v60, v60, 2, s4
	v_lshl_add_u32 v59, v59, 2, s4
	v_lshl_add_u32 v61, v61, 2, s4
	v_lshl_add_u32 v63, v63, 2, s4
	v_med3_i32 v58, v58, s65, v147
	v_lshl_add_u32 v65, v62, 2, s4
	v_lshl_add_u32 v67, v58, 2, s4
	ds_read_b32 v58, v60 offset:512
	ds_read_b32 v60, v59 offset:640
	ds_read_b32 v62, v63 offset:512
	ds_read_b32 v63, v65 offset:512
	ds_read_b32 v59, v64 offset:512
	ds_read_b32 v65, v67 offset:640
	ds_read_b32 v64, v66 offset:640
	ds_read_b32 v61, v61 offset:640
	s_waitcnt lgkmcnt(0)
	v_pk_add_f32 v[32:33], v[32:33], v[62:63]
	v_pk_add_f32 v[30:31], v[30:31], v[58:59]
	v_pk_add_f32 v[28:29], v[28:29], v[54:55]
	v_pk_add_f32 v[26:27], v[26:27], v[50:51]
	v_pk_add_f32 v[24:25], v[24:25], v[46:47]
	v_pk_add_f32 v[22:23], v[22:23], v[42:43]
	v_pk_add_f32 v[20:21], v[20:21], v[38:39]
	v_pk_add_f32 v[18:19], v[18:19], v[34:35]
	v_pk_add_f32 v[16:17], v[16:17], v[64:65]
	v_pk_add_f32 v[14:15], v[14:15], v[60:61]
	v_pk_add_f32 v[12:13], v[12:13], v[56:57]
	v_pk_add_f32 v[10:11], v[10:11], v[52:53]
	v_pk_add_f32 v[8:9], v[8:9], v[48:49]
	v_pk_add_f32 v[6:7], v[6:7], v[44:45]
	v_pk_add_f32 v[4:5], v[4:5], v[40:41]
	v_pk_add_f32 v[2:3], v[2:3], v[36:37]
